# grid barrier poll: all 16 counter loads issued before the first wait (was drip-fed over 4 round trips), on top of the GEMM static-priority version
# baseline (speedup 1.0000x reference)
; __device__ __forceinline__ unsigned xb_ld(unsigned* p)              { return __hip_atomic_load(p, __ATOMIC_RELAXED, __HIP_MEMORY_SCOPE_AGENT); }
; __device__ __forceinline__ void xcd_barrier_complete(unsigned* bar, unsigned x, unsigned& nloc, unsigned& nx) {
;     ...
;     for (;;) {
;         sum = 0u; cnt = 0u; mine = 0u;
; #pragma unroll
;         for (unsigned j = 0; j < 16; ++j) { const unsigned c = xb_ld(&bar[XB_XCNT(j)]); sum += c; cnt += (c > 0u) ? 1u : 0u; mine = (j == x) ? c : mine; }
;         if (sum == G) break;
;         __builtin_amdgcn_s_sleep(1);
;         if ((++sp & 255u) == 0u) { if (xb_ld(&bar[XB_TMO])) break; if (sp > XB_SPIN_CAP) { atomicAdd(&bar[XB_TMO], 1u); break; } }
;     }
.LBB0_1405:
	v_readlane_b32 s2, v253, 1
	v_readlane_b32 s3, v253, 2
	global_load_dword v9, v1, s[68:69] sc1
	global_load_dword v0, v1, s[70:71] sc1
	global_load_dword v2, v1, s[82:83] sc1
	global_load_dword v3, v1, s[88:89] sc1
	global_load_dword v4, v1, s[26:27] sc1
	global_load_dword v5, v1, s[34:35] sc1
	global_load_dword v6, v1, s[22:23] sc1
	global_load_dword v7, v1, s[96:97] sc1
	global_load_dword v8, v1, s[42:43] sc1
	global_load_dword v10, v1, s[2:3] sc1
	v_readlane_b32 s2, v253, 3
	v_readlane_b32 s3, v253, 4
	s_nop 4
	global_load_dword v11, v1, s[2:3] sc1
	v_readlane_b32 s2, v253, 5
	v_readlane_b32 s3, v253, 6
	s_nop 4
	global_load_dword v12, v1, s[2:3] sc1
	v_readlane_b32 s2, v253, 7
	v_readlane_b32 s3, v253, 8
	s_nop 4
	global_load_dword v13, v1, s[2:3] sc1
	v_readlane_b32 s2, v253, 9
	v_readlane_b32 s3, v253, 10
	s_nop 4
	global_load_dword v14, v1, s[2:3] sc1
	v_readlane_b32 s2, v253, 11
	v_readlane_b32 s3, v253, 12
	s_nop 4
	global_load_dword v15, v1, s[2:3] sc1
	v_readlane_b32 s2, v253, 13
	v_readlane_b32 s3, v253, 14
	s_nop 4
	global_load_dword v16, v1, s[2:3] sc1
	s_mov_b64 s[6:7], -1
	s_mov_b64 s[2:3], -1
	s_waitcnt vmcnt(0)
	v_add_u32_e32 v17, v0, v9
	v_add_u32_e32 v17, v17, v2
	v_add_u32_e32 v17, v17, v3
	v_add_u32_e32 v17, v17, v4
	v_add_u32_e32 v17, v17, v5
	v_add_u32_e32 v17, v17, v6
	v_add_u32_e32 v17, v17, v7
	v_add_u32_e32 v17, v17, v8
	v_add_u32_e32 v17, v17, v10
	v_add_u32_e32 v17, v17, v11
	v_add_u32_e32 v17, v17, v12
	v_add_u32_e32 v17, v17, v13
	v_add_u32_e32 v17, v17, v14
	v_add_u32_e32 v17, v17, v15
	v_add_u32_e32 v17, v17, v16
	v_cmp_eq_u32_e32 vcc, s11, v17
	s_cbranch_vccnz .LBB0_1404
	s_and_b32 s2, s12, 0xff
	s_cmp_eq_u32 s2, 0
	s_mov_b64 s[2:3], -1
	s_mov_b64 s[8:9], -1
	s_sleep 1
	s_cbranch_scc1 .LBB0_1409
	s_and_b64 vcc, exec, s[8:9]
	s_cbranch_vccz .LBB0_1404
